# seam 0: cooperative-groups grid.sync replaced by the XCD-hierarchical barrier body of seam 1 (shared via return flag s98); base v_rsl
# speedup vs baseline: 1.0113x; 1.0113x over previous
; #define SEAM(k) do { if (IN(k) && IN((k) + 1)) { if ((k) == 0) grid.sync(); else xcd_barrier(xbar); } } while (0)
; #define PH(k) if (IN(k)) for (int rep_ = 0; rep_ <= ((PROBE_DUP >> (k)) & 1); ++rep_)
;     __host__ __device__ bool next(int i, Unit& u) const {
;         const long L = (long)i * G + c; if (L >= nwg) return false;
;         int wgid = (int)L; { const int q = nwg / NXCD, r = nwg % NXCD, xcd = wgid % NXCD, off = wgid / NXCD; wgid = (xcd < r ? xcd * (q + 1) : r * (q + 1) + (xcd - r) * q) + off; }
;         const int nig = WGM * nN, gid = wgid / nig, fm = gid * WGM, gsz = (nM - fm) < WGM ? (nM - fm) : WGM;
;         u.pm = fm + ((wgid % nig) % gsz); u.pn = (wgid % nig) / gsz; return true;
; __global__ void __launch_bounds__(NTHR, 2) fwd_kernel(Params p) {
;     ...
;     PH(0) { if (rep_) xcd_barrier(xbar); phase_prologue(p, lds); } SEAM(0);
;     PH(1) { if (rep_) xcd_barrier(xbar); pg8::Gemm g{(const bf16*)(ws + WS_XB), (const bf16*)(ws + WS_W_IN), T, N_IN1, DM}; pg8::StaticOrder S; S.init(T, N_IN1, G, bx);
.LBB0_317:
	s_cmp_gt_i32 s31, 1
	s_cselect_b64 s[0:1], -1, 0
	s_and_b64 s[4:5], s[8:9], s[0:1]
	s_andn2_b64 vcc, exec, s[4:5]
	s_cbranch_vccnz .LBB0_329
	v_writelane_b32 v244, s96, 40
	s_mov_b32 s98, 1
	s_branch .Lxseam_enter
.Lxseam_ret0:
.LBB0_329:
	s_mov_b32 s98, 0
	s_cmp_lt_i32 s30, 2
	s_cselect_b64 s[34:35], -1, 0
	s_and_b64 s[0:1], s[34:35], s[0:1]
	s_andn2_b64 vcc, exec, s[0:1]
	v_writelane_b32 v244, s96, 40
	s_cbranch_vccnz .LBB0_422
	s_cmpk_lt_i32 s96, 0xb00
	s_cselect_b64 s[0:1], -1, 0
	s_cmpk_gt_i32 s96, 0xaff
	v_readfirstlane_b32 s4, v144
	s_cbranch_scc1 .LBB0_332
	s_ashr_i32 s3, s96, 31
	s_lshr_b32 s3, s3, 29
	s_add_i32 s3, s96, s3
	s_ashr_i32 s5, s3, 3
	s_and_b32 s3, s3, -8
	s_sub_i32 s3, s96, s3
	s_cmp_lt_i32 s3, 0
	s_movk_i32 s6, 0x161
	s_cselect_b32 s6, s6, 0x160
	s_mul_i32 s3, s3, s6
	s_add_i32 s3, s3, s5
	s_mul_hi_i32 s5, s3, 0x2e8ba2e9
	s_lshr_b32 s6, s5, 31
	s_ashr_i32 s5, s5, 5
	s_add_i32 s5, s5, s6
	s_lshl_b32 s6, s5, 3
	s_mulk_i32 s5, 0xb0
	s_sub_i32 s3, s3, s5
	s_sext_i32_i16 s5, s3
	s_bfe_u32 s5, s5, 0x3001c
	s_add_i32 s5, s3, s5
	s_sext_i32_i16 s7, s5
	s_and_b32 s5, s5, 0xfff8
	s_sub_i32 s3, s3, s5
	s_sext_i32_i16 s3, s3
	s_add_i32 s6, s6, s3
	s_ashr_i32 s8, s7, 3

; __device__ __forceinline__ unsigned xb_ld(unsigned* p)              { return __hip_atomic_load(p, __ATOMIC_RELAXED, __HIP_MEMORY_SCOPE_AGENT); }
; __device__ __forceinline__ void xcd_barrier_complete(unsigned* bar, unsigned x, unsigned& nloc, unsigned& nx) {
;     const unsigned G = gridDim.x * gridDim.y * gridDim.z;
;     unsigned sum, cnt, mine, sp = 0u;
;     for (;;) {
;         sum = 0u; cnt = 0u; mine = 0u;
; #pragma unroll
;         for (unsigned j = 0; j < 16; ++j) { const unsigned c = xb_ld(&bar[XB_XCNT(j)]); sum += c; cnt += (c > 0u) ? 1u : 0u; mine = (j == x) ? c : mine; }
; __device__ __forceinline__ void xcd_barrier(const XcdBarrier& b) {
;     asm volatile("s_waitcnt vmcnt(0)" ::: "memory");
;     __syncthreads();
;     if (threadIdx.x == 0) {
;         unsigned* bar = b.bar;
;         __builtin_amdgcn_s_waitcnt(0);
;         unsigned nloc = b.st[0], nx = b.st[1];
;         if (nloc == 0u) { xcd_barrier_complete(bar, b.x, nloc, nx); b.st[0] = nloc; b.st[1] = nx; }
.Lxseam_enter:
	s_waitcnt vmcnt(0)
	s_waitcnt lgkmcnt(0)
	s_barrier
	s_mov_b64 s[4:5], exec
	v_readlane_b32 s6, v244, 20
	v_readlane_b32 s7, v244, 21
	s_and_b64 s[6:7], s[4:5], s[6:7]
	s_mov_b64 exec, s[6:7]
	s_cbranch_execz .LBB0_476
	s_add_i32 s3, 0, 0x23040
	v_mov_b32_e32 v0, s3
	s_waitcnt vmcnt(0) expcnt(0) lgkmcnt(0)
	ds_read_b32 v2, v0
	s_add_i32 s3, 0, 0x23044
	v_mov_b32_e32 v0, s3
	ds_read_b32 v0, v0
	s_waitcnt lgkmcnt(1)
	v_cmp_ne_u32_e32 vcc, 0, v2
	s_cbranch_vccnz .LBB0_440
	s_add_u32 s6, s28, 0x8700200
	s_addc_u32 s7, s29, 0
	s_add_u32 s8, s28, 0x8700400
	s_addc_u32 s9, s29, 0
	s_add_u32 s10, s28, 0x8700500
	s_addc_u32 s11, s29, 0
	s_add_u32 s12, s28, 0x8700600
	s_addc_u32 s13, s29, 0
	s_add_u32 s14, s28, 0x8700700
	s_addc_u32 s15, s29, 0
	s_add_u32 s16, s28, 0x8700800
	s_addc_u32 s17, s29, 0
	s_add_u32 s18, s28, 0x8700900
	s_addc_u32 s19, s29, 0
	s_add_u32 s52, s28, 0x8700a00
	s_addc_u32 s53, s29, 0
	s_add_u32 s68, s28, 0x8700b00
	s_addc_u32 s69, s29, 0
	s_add_u32 s70, s28, 0x8700c00
	s_addc_u32 s71, s29, 0
	s_add_u32 s72, s28, 0x8700d00
	s_addc_u32 s73, s29, 0
	s_add_u32 s78, s28, 0x8700e00
	s_addc_u32 s79, s29, 0
	s_add_u32 s82, s28, 0x8700f00
	s_addc_u32 s83, s29, 0
	s_add_u32 s84, s28, 0x8701000
	s_addc_u32 s85, s29, 0
	s_add_u32 s86, s28, 0x8701100
	s_addc_u32 s87, s29, 0
	s_mov_b32 s37, s2
	v_readlane_b32 s2, v244, 0
	s_add_u32 s88, s28, 0x8701200
	v_readlane_b32 s3, v244, 1
	s_addc_u32 s89, s29, 0
	s_mul_i32 s3, s3, s94
	s_add_u32 s90, s28, 0x8701300
	s_mov_b64 s[38:39], s[92:93]
	s_mov_b32 s40, s94
	s_mul_i32 s3, s3, s2
	s_addc_u32 s91, s29, 0
	s_mov_b32 s33, 1
	v_mov_b32_e32 v16, 0
	s_branch .LBB0_428

; __device__ __forceinline__ void xcd_barrier(const XcdBarrier& b) {
;     ...
;     }
;     __syncthreads();
.LBB0_476:
	s_or_b64 exec, exec, s[4:5]
	s_waitcnt lgkmcnt(0)
	s_barrier
	s_cmp_eq_u32 s98, 1
	s_cbranch_scc1 .Lxseam_ret0
